# SWA: first key tile (left window edge) bias add also batched: 16 ds_read_b32 + one wait + add/cndmask with the precomputed lane masks, when the block is not the first of the sequence
# baseline (speedup 1.0000x reference)
; #define LAS __attribute__((address_space(3)))
; #define MFMA32(a, b, c) __builtin_amdgcn_mfma_f32_32x32x16_bf16((a), (b), (c), 0, 0, 0)
; __device__ __forceinline__ int crow(int i, int hh) { return (i & 3) + 8 * (i >> 2) + 4 * hh; }
; __device__ __forceinline__ void swa_unit(LAS unsigned char* lds, const bf16_t* Z1, const bf16_t* VTA, const float* bias2, const float* sinks, bf16_t* OA, int b, int kvh, int qblk, int wv) {
;     ...
;         const int q0w = 64 * half + 32 * sub;
;         bf16x8 qf[4];
;         { const bf16_t* qp = Z1 + (rowbase + Q0 + q0w + r) * N1 + head * 64 + 8 * hh;
; #pragma unroll
;           for (int s = 0; s < 4; ++s) qf[s] = *(const bf16x8*)(qp + 16 * s); }
;         f32x16 o0, o1;
; #pragma unroll
;         for (int i = 0; i < 16; ++i) { o0[i] = 0.f; o1[i] = 0.f; }
;         float m = sink2, l = (hh == 0) ? 1.f : 0.f;
; #pragma unroll
;         for (int kt = 0; kt < 5; ++kt) {
;             const int kb = q0w + 32 * kt;
;             if (Q0 == 0 && kb + 31 < 128) continue;
;             f32x16 sc;
; #pragma unroll
;             for (int i = 0; i < 16; ++i) sc[i] = 0.f;
; #pragma unroll
;             for (int s = 0; s < 4; ++s) { const bf16x8 a = *(const LAS bf16x8*)(lds + (kb + r) * SK_ROW + s * 32 + hh * 16); sc = MFMA32(a, qf[s], sc); }
; #pragma unroll
;             for (int i = 0; i < 16; ++i) { const int c = crow(i, hh), dist = 128 - 32 * kt + r - c;
;                 const bool ok = (dist >= 0) && (dist < 128) && (Q0 > 0 || kb + c >= 128);
;                 sc[i] = ok ? sc[i] + bl[dist & 127] : -INFINITY; }
.LBB0_691:
	s_or_b32 s30, s16, s12
	s_ashr_i32 s31, s30, 31
	v_lshl_add_u64 v[74:75], v[66:67], 0, s[30:31]
	v_mad_u64_u32 v[2:3], s[16:17], v74, s27, v[68:69]
	v_mov_b32_e32 v0, v3
	v_mad_u64_u32 v[4:5], s[16:17], v75, s27, v[0:1]
	v_mov_b32_e32 v3, v4
	global_load_dwordx4 v[62:65], v[2:3], off
	global_load_dwordx4 v[58:61], v[2:3], off offset:32
	global_load_dwordx4 v[54:57], v[2:3], off offset:64
	global_load_dwordx4 v[50:53], v[2:3], off offset:96
	s_or_b32 s16, s30, 31
	s_cmpk_lt_i32 s16, 0x80
	s_cselect_b64 s[16:17], -1, 0
	s_and_b64 s[16:17], s[8:9], s[16:17]
	s_and_b64 vcc, exec, s[16:17]
	s_cbranch_vccnz .LBB0_757
	v_or_b32_e32 v0, s30, v71
	v_mad_u64_u32 v[22:23], s[16:17], v0, s19, v[70:71]
	ds_read_b128 v[2:5], v22
	ds_read_b128 v[18:21], v22 offset:32
	v_mov_b32_e32 v0, 0xff800000
	s_waitcnt vmcnt(3) lgkmcnt(1)
	v_mfma_f32_32x32x16_bf16 v[2:17], v[2:5], v[62:65], 0
	s_waitcnt vmcnt(2) lgkmcnt(0)
	v_mfma_f32_32x32x16_bf16 v[2:17], v[18:21], v[58:61], v[2:17]
	ds_read_b128 v[18:21], v22 offset:64
	s_waitcnt vmcnt(1) lgkmcnt(0)
	v_mfma_f32_32x32x16_bf16 v[2:17], v[18:21], v[54:57], v[2:17]
	ds_read_b128 v[18:21], v22 offset:96
	s_waitcnt vmcnt(0) lgkmcnt(0)
	v_mfma_f32_32x32x16_bf16 v[2:17], v[18:21], v[50:53], v[2:17]
	v_mov_b32_e32 v18, 0xff800000
	s_cmp_eq_u64 s[10:11], -1
	s_cbranch_scc1 .Lswa_fastk0
	s_and_saveexec_b64 s[16:17], s[36:37]
	s_cbranch_execz .LBB0_696
	v_or_b32_e32 v18, s30, v78
	v_cmp_lt_i32_e32 vcc, s3, v18
	s_or_b64 s[22:23], s[10:11], vcc
	v_mov_b32_e32 v18, 0xff800000
	s_and_saveexec_b64 vcc, s[22:23]
	s_cbranch_execz .LBB0_695
	ds_read_b32 v18, v80 offset:512
	s_waitcnt lgkmcnt(0)
	s_nop 0
	v_add_f32_e32 v18, v2, v18

; #define LAS __attribute__((address_space(3)))
; #define MFMA32(a, b, c) __builtin_amdgcn_mfma_f32_32x32x16_bf16((a), (b), (c), 0, 0, 0)
; __device__ __forceinline__ float xhalf_max(float x) { float a, b; xhalf_swap(x, a, b); float m; asm("v_max3_f32 %0, %1, %2, %3" : "=v"(m) : "v"(x), "v"(a), "v"(b)); return m; }
; __device__ __forceinline__ void swa_unit(LAS unsigned char* lds, const bf16_t* Z1, const bf16_t* VTA, const float* bias2, const float* sinks, bf16_t* OA, int b, int kvh, int qblk, int wv) {
;     ...
;             const float mx = xhalf_max(max16(sc));
;             float alpha = 1.0f;
;             if (__any(mx > m + RESCALE_THR)) {
;                 const float mn = fmaxf(m, mx); alpha = __builtin_amdgcn_exp2f(m - mn); m = mn;
; #pragma unroll
;                 for (int i = 0; i < 16; ++i) { o0[i] *= alpha; o1[i] *= alpha; }
;             }
;             float ps = 0.f;
; #pragma unroll
;             for (int i = 0; i < 16; ++i) { sc[i] = __builtin_amdgcn_exp2f(sc[i] - m); ps += sc[i]; }
;             l = l * alpha + ps;
;             const LAS unsigned char* vb = lds + SK_BYTES + r * SV_ROW + kb * 2 + hh * 16;
; #pragma unroll
;             for (int ks = 0; ks < 2; ++ks) {
;                 const bf16x8 pb = pack8(sc, 8 * ks);
;                 const bf16x8 v0 = *(const LAS bf16x8*)(vb + ks * 32), v1 = *(const LAS bf16x8*)(vb + 32 * SV_ROW + ks * 32);
;                 o0 = MFMA32(v0, pb, o0); o1 = MFMA32(v1, pb, o1);
;             }
.Lswa_endk0:
	v_max3_f32 v2, v18, v0, v20
	v_max3_f32 v3, v19, v22, v21
	v_max3_f32 v4, v24, v23, v26
	v_max3_f32 v5, v25, v28, v27
	v_max3_f32 v6, v35, v34, v37
	v_lshl_add_u32 v138, s30, 1, v79
	v_max3_f32 v2, v2, v3, v4
	v_max3_f32 v3, v5, v6, v36
	s_nop 0
	v_max3_f32 v2, v2, v3, v36
	s_nop 0
	v_mov_b32_e32 v3, v2
	v_mov_b32_e32 v4, v2
	s_nop 1
	v_permlane32_swap_b32 v3, v4
	s_nop 1
	ds_read_b128 v[38:41], v138 offset:36864
	ds_read_b128 v[46:49], v138 offset:53760
	v_max3_f32 v2, v2, v3, v4
	v_max_f32_e32 v4, v76, v76
	v_cmp_gt_f32_e32 vcc, v2, v111
	v_max_f32_e32 v3, v2, v2
	s_cmp_eq_u64 vcc, 0
	v_max_f32_e32 v29, v4, v3
	s_cselect_b64 vcc, -1, 0
	v_cndmask_b32_e32 v128, v29, v76, vcc
	v_sub_f32_e32 v18, v18, v128
	v_exp_f32_e32 v129, v18
	v_sub_f32_e32 v18, v20, v128
	v_exp_f32_e32 v130, v18
	v_sub_f32_e32 v18, v19, v128
	v_exp_f32_e32 v131, v18
	v_sub_f32_e32 v18, v22, v128
	v_sub_f32_e32 v3, v76, v29
	v_exp_f32_e32 v132, v18
	v_sub_f32_e32 v18, v21, v128
	v_exp_f32_e32 v127, v3
	v_exp_f32_e32 v133, v18
	v_sub_f32_e32 v18, v24, v128
	v_sub_f32_e32 v0, v0, v128
	v_exp_f32_e32 v134, v18
	v_sub_f32_e32 v18, v23, v128
	v_exp_f32_e32 v0, v0
	v_exp_f32_e32 v135, v18
	v_mul_f32_e32 v2, 0, v127
	v_sub_f32_e32 v18, v26, v128
	v_cndmask_b32_e64 v2, v2, 0, vcc
	v_exp_f32_e32 v136, v18
	v_sub_f32_e32 v18, v25, v128
	v_mov_b32_e32 v3, v2
	v_mov_b32_e32 v4, v2
	v_mov_b32_e32 v5, v2
	v_mov_b32_e32 v6, v2
	v_mov_b32_e32 v7, v2
	v_mov_b32_e32 v8, v2
	v_mov_b32_e32 v9, v2
	v_mov_b32_e32 v10, v2
	v_mov_b32_e32 v11, v2
	v_mov_b32_e32 v12, v2
	v_mov_b32_e32 v13, v2
	v_mov_b32_e32 v14, v2
	v_mov_b32_e32 v15, v2
	v_mov_b32_e32 v16, v2
	v_mov_b32_e32 v17, v2
	v_exp_f32_e32 v137, v18
	v_sub_f32_e32 v18, v28, v128
	v_cvt_pk_bf16_f32 v42, v129, v0
	v_cvt_pk_bf16_f32 v43, v130, v131
	v_cvt_pk_bf16_f32 v44, v132, v133
	v_cvt_pk_bf16_f32 v45, v134, v135
	v_exp_f32_e32 v139, v18
	v_sub_f32_e32 v140, v27, v128
	s_waitcnt lgkmcnt(1)
	v_mfma_f32_32x32x16_bf16 v[18:33], v[38:41], v[42:45], v[2:17]
	ds_read_b128 v[38:41], v138 offset:36896
	v_sub_f32_e32 v34, v34, v128
	v_exp_f32_e32 v142, v34
	v_sub_f32_e32 v34, v37, v128
	v_sub_f32_e32 v35, v35, v128
	v_exp_f32_e32 v140, v140
	v_exp_f32_e32 v141, v35
	s_waitcnt lgkmcnt(1)
	v_mfma_f32_32x32x16_bf16 v[2:17], v[46:49], v[42:45], v[2:17]
	v_exp_f32_e32 v42, v34
	v_sub_f32_e32 v34, v36, v128
	v_exp_f32_e32 v43, v34
	v_cvt_pk_bf16_f32 v34, v136, v137
	v_cvt_pk_bf16_f32 v35, v139, v140
	v_cvt_pk_bf16_f32 v36, v141, v142
	v_cvt_pk_bf16_f32 v37, v42, v43
	v_cndmask_b32_e64 v44, v127, 1.0, vcc
	s_waitcnt lgkmcnt(0)
	v_mfma_f32_32x32x16_bf16 v[18:33], v[38:41], v[34:37], v[18:33]
	ds_read_b128 v[38:41], v138 offset:53792
	s_waitcnt lgkmcnt(0)
	v_mfma_f32_32x32x16_bf16 v[2:17], v[38:41], v[34:37], v[2:17]
	v_add_f32_e32 v34, 0, v129
	v_add_f32_e32 v0, v0, v34
	v_add_f32_e32 v0, v130, v0
	v_add_f32_e32 v0, v131, v0
	v_add_f32_e32 v0, v132, v0
	v_add_f32_e32 v0, v133, v0
	v_add_f32_e32 v0, v134, v0
	v_add_f32_e32 v0, v135, v0
	v_add_f32_e32 v0, v136, v0
	v_add_f32_e32 v0, v137, v0
	v_add_f32_e32 v0, v139, v0
	v_add_f32_e32 v0, v140, v0
	v_add_f32_e32 v0, v141, v0
	v_add_f32_e32 v0, v142, v0
	v_add_f32_e32 v0, v42, v0
	v_add_f32_e32 v127, v43, v0
	v_fmac_f32_e32 v127, v77, v44
	s_branch .LBB0_758

; __device__ __forceinline__ int crow(int i, int hh) { return (i & 3) + 8 * (i >> 2) + 4 * hh; }
; __device__ __forceinline__ void swa_unit(LAS unsigned char* lds, const bf16_t* Z1, const bf16_t* VTA, const float* bias2, const float* sinks, bf16_t* OA, int b, int kvh, int qblk, int wv) {
;     ...
;             for (int i = 0; i < 16; ++i) { const int c = crow(i, hh), dist = 128 - 32 * kt + r - c;
;                 const bool ok = (dist >= 0) && (dist < 128) && (Q0 > 0 || kb + c >= 128);
;                 sc[i] = ok ? sc[i] + bl[dist & 127] : -INFINITY; }
.Lswa_fastk0:
	ds_read_b32 v144, v80 offset:512
	ds_read_b32 v145, v82 offset:512
	ds_read_b32 v146, v84 offset:512
	ds_read_b32 v147, v86 offset:512
	ds_read_b32 v148, v88 offset:512
	ds_read_b32 v149, v90 offset:512
	ds_read_b32 v150, v92 offset:512
	ds_read_b32 v151, v94 offset:512
	ds_read_b32 v152, v96 offset:512
	ds_read_b32 v153, v98 offset:512
	ds_read_b32 v154, v100 offset:512
	ds_read_b32 v155, v102 offset:512
	ds_read_b32 v156, v104 offset:512
	ds_read_b32 v157, v106 offset:512
	ds_read_b32 v158, v108 offset:512
	ds_read_b32 v159, v110 offset:512
	v_mov_b32_e32 v160, 0xff800000
	s_waitcnt lgkmcnt(0)
	v_add_f32_e32 v144, v2, v144
	v_cndmask_b32_e64 v18, v160, v144, s[36:37]
	v_add_f32_e32 v145, v3, v145
	v_cndmask_b32_e64 v0, v160, v145, s[38:39]
	v_add_f32_e32 v146, v4, v146
	v_cndmask_b32_e64 v20, v160, v146, s[40:41]
	v_add_f32_e32 v147, v5, v147
	v_cndmask_b32_e64 v19, v160, v147, s[42:43]
	v_add_f32_e32 v148, v6, v148
	v_cndmask_b32_e64 v22, v160, v148, s[44:45]
	v_add_f32_e32 v149, v7, v149
	v_cndmask_b32_e64 v21, v160, v149, s[46:47]
	v_add_f32_e32 v150, v8, v150
	v_cndmask_b32_e64 v24, v160, v150, s[48:49]
	v_add_f32_e32 v151, v9, v151
	v_cndmask_b32_e64 v23, v160, v151, s[50:51]
	v_add_f32_e32 v152, v10, v152
	v_cndmask_b32_e64 v26, v160, v152, s[52:53]
	v_add_f32_e32 v153, v11, v153
	v_cndmask_b32_e64 v25, v160, v153, s[54:55]
	v_add_f32_e32 v154, v12, v154
	v_cndmask_b32_e64 v28, v160, v154, s[56:57]
	v_add_f32_e32 v155, v13, v155
	v_cndmask_b32_e64 v27, v160, v155, s[58:59]
	v_add_f32_e32 v156, v14, v156
	v_cndmask_b32_e64 v35, v160, v156, s[60:61]
	v_add_f32_e32 v157, v15, v157
	v_cndmask_b32_e64 v34, v160, v157, s[62:63]
	v_add_f32_e32 v158, v16, v158
	v_cndmask_b32_e64 v37, v160, v158, s[64:65]
	v_add_f32_e32 v159, v17, v159
	v_cndmask_b32_e64 v36, v160, v159, s[66:67]
	s_branch .Lswa_endk0
